# v11 + attention QK^T: K fragments prefetched 5 k-steps ahead using 7 extra fragment buffers in free VGPRs
# baseline (speedup 1.0000x reference)
.Lat_qk:
	ds_read_b128 v[190:193], v187
	ds_read_b128 v[194:197], v187 offset:12800
	ds_read_b128 v[198:201], v187 offset:32
	ds_read_b128 v[214:217], v187 offset:12832
	ds_read_b128 v[218:221], v187 offset:64
	ds_read_b128 v[222:225], v187 offset:12864
	ds_read_b128 v[226:229], v187 offset:96
	ds_read_b128 v[230:233], v187 offset:12896
	ds_read_b128 v[234:237], v187 offset:128
	ds_read_b128 v[238:241], v187 offset:12928
	s_waitcnt lgkmcnt(9)
	v_mfma_f32_32x32x16_bf16 v[80:95], v[190:193], v[96:99], 0
	ds_read_b128 v[190:193], v187 offset:160
	s_waitcnt lgkmcnt(9)
	v_mfma_f32_32x32x16_bf16 v[64:79], v[194:197], v[96:99], 0
	ds_read_b128 v[194:197], v187 offset:12960
	s_waitcnt lgkmcnt(9)
	v_mfma_f32_32x32x16_bf16 v[80:95], v[198:201], v[100:103], v[80:95]
	ds_read_b128 v[198:201], v187 offset:192
	s_waitcnt lgkmcnt(9)
	v_mfma_f32_32x32x16_bf16 v[64:79], v[214:217], v[100:103], v[64:79]
	ds_read_b128 v[214:217], v187 offset:12992
	s_waitcnt lgkmcnt(9)
	v_mfma_f32_32x32x16_bf16 v[80:95], v[218:221], v[104:107], v[80:95]
	ds_read_b128 v[218:221], v187 offset:224
	s_waitcnt lgkmcnt(9)
	v_mfma_f32_32x32x16_bf16 v[64:79], v[222:225], v[104:107], v[64:79]
	ds_read_b128 v[222:225], v187 offset:13024
	s_waitcnt lgkmcnt(9)
	v_mfma_f32_32x32x16_bf16 v[80:95], v[226:229], v[108:111], v[80:95]
	ds_read_b128 v[226:229], v187 offset:256
	s_waitcnt lgkmcnt(9)
	v_mfma_f32_32x32x16_bf16 v[64:79], v[230:233], v[108:111], v[64:79]
	ds_read_b128 v[230:233], v187 offset:13056
	s_waitcnt lgkmcnt(9)
	v_mfma_f32_32x32x16_bf16 v[80:95], v[234:237], v[112:115], v[80:95]
	ds_read_b128 v[234:237], v187 offset:288
	s_waitcnt lgkmcnt(9)
	v_mfma_f32_32x32x16_bf16 v[64:79], v[238:241], v[112:115], v[64:79]
	ds_read_b128 v[238:241], v187 offset:13088
	s_waitcnt lgkmcnt(9)
	v_mfma_f32_32x32x16_bf16 v[80:95], v[190:193], v[116:119], v[80:95]
	ds_read_b128 v[190:193], v187 offset:320
	s_waitcnt lgkmcnt(9)
	v_mfma_f32_32x32x16_bf16 v[64:79], v[194:197], v[116:119], v[64:79]
	ds_read_b128 v[194:197], v187 offset:13120
	s_waitcnt lgkmcnt(9)
	v_mfma_f32_32x32x16_bf16 v[80:95], v[198:201], v[120:123], v[80:95]
	ds_read_b128 v[198:201], v187 offset:352
	s_waitcnt lgkmcnt(9)
	v_mfma_f32_32x32x16_bf16 v[64:79], v[214:217], v[120:123], v[64:79]
	ds_read_b128 v[214:217], v187 offset:13152
	s_waitcnt lgkmcnt(9)
	v_mfma_f32_32x32x16_bf16 v[80:95], v[218:221], v[124:127], v[80:95]
	s_waitcnt lgkmcnt(8)
	v_mfma_f32_32x32x16_bf16 v[64:79], v[222:225], v[124:127], v[64:79]
	s_waitcnt lgkmcnt(7)
	v_mfma_f32_32x32x16_bf16 v[80:95], v[226:229], v[128:131], v[80:95]
	s_waitcnt lgkmcnt(6)
	v_mfma_f32_32x32x16_bf16 v[64:79], v[230:233], v[128:131], v[64:79]
	s_waitcnt lgkmcnt(5)
	v_mfma_f32_32x32x16_bf16 v[80:95], v[234:237], v[132:135], v[80:95]
	s_waitcnt lgkmcnt(4)
	v_mfma_f32_32x32x16_bf16 v[64:79], v[238:241], v[132:135], v[64:79]
	s_waitcnt lgkmcnt(3)
	v_mfma_f32_32x32x16_bf16 v[80:95], v[190:193], v[136:139], v[80:95]
	s_waitcnt lgkmcnt(2)
	v_mfma_f32_32x32x16_bf16 v[64:79], v[194:197], v[136:139], v[64:79]
	s_waitcnt lgkmcnt(1)
	v_mfma_f32_32x32x16_bf16 v[80:95], v[198:201], v[140:143], v[80:95]
	s_waitcnt lgkmcnt(0)
	v_mfma_f32_32x32x16_bf16 v[64:79], v[214:217], v[140:143], v[64:79]
	s_cbranch_execz .LBB0_1535
